# spatial-gating MFMA loop: the 1-4 serialized per-ks weight loads hoisted before the loop (one round trip per group), on top of the full stack v42
# speedup vs baseline: 1.0132x; 1.0017x over previous
; #define GAS __attribute__((address_space(1)))
; DI void phase_mix(const Ctx& C, bf16_t* Z, const float* lse_, int L, bool dry) {
;     ...
;         f32x4 acc[8];
; #pragma unroll
;         for (int ct = 0; ct < 8; ++ct) acc[ct] = (f32x4){0.f, 0.f, 0.f, 0.f};
;         const bf16_t* wrow = sgw + (size_t)(g * 128 + 16 * w + fr) * 128 + 8 * fq;
;         const int nks = (w >> 1) + 1;
;         for (int ks = 0; ks < nks; ++ks) {
;             const bf16x8 bw = *(const GAS bf16x8*)(wrow + 32 * ks);
.LBB0_196:
	v_mov_b32_e32 v16, 0
	v_mov_b64_e32 v[88:89], v[68:69]
	global_load_dwordx4 v[120:123], v[88:89], off
	global_load_dwordx4 v[144:147], v[88:89], off offset:64
	global_load_dwordx4 v[148:151], v[88:89], off offset:128
	global_load_dwordx4 v[152:155], v[88:89], off offset:192
	v_mov_b32_e32 v55, v92
	s_mov_b32 s1, s30
	v_mov_b32_e32 v17, v16
	v_mov_b32_e32 v18, v16
	v_mov_b32_e32 v19, v16
	v_mov_b32_e32 v20, v16
	v_mov_b32_e32 v21, v16
	v_mov_b32_e32 v22, v16
	v_mov_b32_e32 v23, v16
	v_mov_b32_e32 v24, v16
	v_mov_b32_e32 v25, v16
	v_mov_b32_e32 v26, v16
	v_mov_b32_e32 v27, v16
	v_mov_b32_e32 v28, v16
	v_mov_b32_e32 v29, v16
	v_mov_b32_e32 v30, v16
	v_mov_b32_e32 v31, v16
	v_mov_b32_e32 v32, v16
	v_mov_b32_e32 v33, v16
	v_mov_b32_e32 v34, v16
	v_mov_b32_e32 v35, v16
	v_mov_b32_e32 v36, v16
	v_mov_b32_e32 v37, v16
	v_mov_b32_e32 v38, v16
	v_mov_b32_e32 v39, v16
	v_mov_b32_e32 v40, v16
	v_mov_b32_e32 v41, v16
	v_mov_b32_e32 v42, v16
	v_mov_b32_e32 v43, v16
	v_mov_b32_e32 v44, v16
	v_mov_b32_e32 v45, v16
	v_mov_b32_e32 v46, v16
	v_mov_b32_e32 v47, v16
; __device__ __forceinline__ unsigned cvt_pk_bf16(float lo, float hi) { unsigned r; asm volatile("v_cvt_pk_bf16_f32 %0, %1, %2" : "=v"(r) : "v"(lo), "v"(hi)); return r; }
; #define LAS __attribute__((address_space(3)))
; #define GAS __attribute__((address_space(1)))
; DI float bf_lo(unsigned w) { return __uint_as_float(w << 16); }
; DI float bf_hi(unsigned w) { return __uint_as_float(w & 0xffff0000u); }
; DI void phase_mix(const Ctx& C, bf16_t* Z, const float* lse_, int L, bool dry) {
;     ...
;         for (int ks = 0; ks < nks; ++ks) {
;             const bf16x8 bw = *(const GAS bf16x8*)(wrow + 32 * ks);
; #pragma unroll
;             for (int ct = 0; ct < 8; ++ct) {
;                 const bf16x8 av = *(const LAS bf16x8*)(Vt2 + (16 * ct + fr) * 136 + ((32 * ks + 8 * fq) ^ (((2 * ct + (fr >> 3)) & 15) << 3)));
;                 acc[ct] = __builtin_amdgcn_mfma_f32_16x16x32_bf16(av, bw, acc[ct], 0, 0, 0);
;             }
;         }
; #pragma unroll
;         for (int ct = 0; ct < 8; ++ct) {
;             const u32x2 uv = uq[ct]; u32x2 wv;
;             wv.x = cvt_pk_bf16(bf_lo(uv.x) * (acc[ct][0] + bias), bf_hi(uv.x) * (acc[ct][1] + bias));
;             wv.y = cvt_pk_bf16(bf_lo(uv.y) * (acc[ct][2] + bias), bf_hi(uv.y) * (acc[ct][3] + bias));
;             *(GAS u32x2*)(dry ? dummy + 16 * ct : up + 16 * ct) = wv;
;         }
;         __syncthreads();
;         }
.LBB0_197:
	v_xor_b32_e32 v57, v55, v93
	v_xor_b32_e32 v115, v55, v103
	v_xor_b32_e32 v124, v55, v106
	v_xor_b32_e32 v125, v55, v107
	v_xor_b32_e32 v126, v55, v108
	v_xor_b32_e32 v127, v55, v109
	v_lshl_add_u32 v57, v57, 1, v102
	v_lshl_add_u32 v115, v115, 1, v102
	v_lshl_add_u32 v132, v124, 1, v102
	v_lshl_add_u32 v133, v125, 1, v102
	v_lshl_add_u32 v134, v126, 1, v102
	v_lshl_add_u32 v135, v127, 1, v102
	ds_read_b128 v[124:127], v57
	ds_read_b128 v[128:131], v115 offset:4352
	v_xor_b32_e32 v116, v55, v104
	v_xor_b32_e32 v117, v55, v105
	v_lshl_add_u32 v116, v116, 1, v102
	v_lshl_add_u32 v117, v117, 1, v102
	s_add_i32 s1, s1, -1
	v_add_u32_e32 v55, 32, v55
	s_cmp_eq_u32 s1, 0
	v_lshl_add_u64 v[88:89], v[88:89], 0, 64
	s_waitcnt vmcnt(0) lgkmcnt(1)
	v_mfma_f32_16x16x32_bf16 v[44:47], v[124:127], v[120:123], v[44:47]
	ds_read_b128 v[124:127], v116 offset:8704
	s_waitcnt lgkmcnt(1)
	v_mfma_f32_16x16x32_bf16 v[40:43], v[128:131], v[120:123], v[40:43]
	ds_read_b128 v[128:131], v117 offset:13056
	s_waitcnt lgkmcnt(1)
	v_mfma_f32_16x16x32_bf16 v[36:39], v[124:127], v[120:123], v[36:39]
	ds_read_b128 v[124:127], v132 offset:17408
	s_waitcnt lgkmcnt(1)
	v_mfma_f32_16x16x32_bf16 v[32:35], v[128:131], v[120:123], v[32:35]
	ds_read_b128 v[128:131], v133 offset:21760
	s_waitcnt lgkmcnt(1)
	v_mfma_f32_16x16x32_bf16 v[28:31], v[124:127], v[120:123], v[28:31]
	ds_read_b128 v[124:127], v134 offset:26112
	s_waitcnt lgkmcnt(1)
	v_mfma_f32_16x16x32_bf16 v[24:27], v[128:131], v[120:123], v[24:27]
	ds_read_b128 v[128:131], v135 offset:30464
	s_waitcnt lgkmcnt(1)
	v_mfma_f32_16x16x32_bf16 v[20:23], v[124:127], v[120:123], v[20:23]
	s_waitcnt lgkmcnt(0)
	v_mfma_f32_16x16x32_bf16 v[16:19], v[128:131], v[120:123], v[16:19]
	s_nop 1
	v_mov_b32_e32 v120, v144
	v_mov_b32_e32 v121, v145
	v_mov_b32_e32 v122, v146
	v_mov_b32_e32 v123, v147
	v_mov_b32_e32 v144, v148
	v_mov_b32_e32 v145, v149
	v_mov_b32_e32 v146, v150
	v_mov_b32_e32 v147, v151
	v_mov_b32_e32 v148, v152
	v_mov_b32_e32 v149, v153
	v_mov_b32_e32 v150, v154
	v_mov_b32_e32 v151, v155
	s_cbranch_scc0 .LBB0_197
	v_lshlrev_b32_e32 v55, 16, v86
	v_add_f32_e32 v44, v53, v44
	v_mul_f32_e32 v44, v44, v55
	v_and_b32_e32 v55, 0xffff0000, v86
	v_add_f32_e32 v45, v53, v45
	v_mul_f32_e32 v45, v45, v55
	v_cvt_pk_bf16_f32 v44, v44, v45
	v_lshlrev_b32_e32 v45, 16, v87
	v_add_f32_e32 v46, v53, v46
	v_mul_f32_e32 v45, v46, v45
	v_and_b32_e32 v46, 0xffff0000, v87
	v_add_f32_e32 v47, v53, v47
	v_mul_f32_e32 v46, v47, v46
	v_cvt_pk_bf16_f32 v45, v45, v46
	global_store_dwordx2 v[70:71], v[44:45], off
	v_lshlrev_b32_e32 v44, 16, v84
	v_add_f32_e32 v40, v53, v40
	v_mul_f32_e32 v40, v40, v44
	v_and_b32_e32 v44, 0xffff0000, v84
	v_add_f32_e32 v41, v53, v41
	v_mul_f32_e32 v41, v41, v44
	v_cvt_pk_bf16_f32 v40, v40, v41
	v_lshlrev_b32_e32 v41, 16, v85
	v_add_f32_e32 v42, v53, v42
	v_mul_f32_e32 v41, v42, v41
	v_and_b32_e32 v42, 0xffff0000, v85
	v_add_f32_e32 v43, v53, v43
	v_mul_f32_e32 v42, v43, v42
	v_cvt_pk_bf16_f32 v41, v41, v42
	global_store_dwordx2 v[70:71], v[40:41], off offset:32
	v_lshlrev_b32_e32 v40, 16, v82
	v_add_f32_e32 v36, v53, v36
	v_mul_f32_e32 v36, v36, v40
	v_and_b32_e32 v40, 0xffff0000, v82
	v_add_f32_e32 v37, v53, v37
	v_mul_f32_e32 v37, v37, v40
	v_cvt_pk_bf16_f32 v36, v36, v37
	v_lshlrev_b32_e32 v37, 16, v83
	v_add_f32_e32 v38, v53, v38
	v_mul_f32_e32 v37, v38, v37
	v_and_b32_e32 v38, 0xffff0000, v83
	v_add_f32_e32 v39, v53, v39
	v_mul_f32_e32 v38, v39, v38
	v_cvt_pk_bf16_f32 v37, v37, v38
	global_store_dwordx2 v[70:71], v[36:37], off offset:64
	v_lshlrev_b32_e32 v36, 16, v80
	v_add_f32_e32 v32, v53, v32
	v_mul_f32_e32 v32, v32, v36
	v_and_b32_e32 v36, 0xffff0000, v80
	v_add_f32_e32 v33, v53, v33
	v_mul_f32_e32 v33, v33, v36
	v_cvt_pk_bf16_f32 v32, v32, v33
	v_lshlrev_b32_e32 v33, 16, v81
	v_add_f32_e32 v34, v53, v34
	v_mul_f32_e32 v33, v34, v33
	v_and_b32_e32 v34, 0xffff0000, v81
	v_add_f32_e32 v35, v53, v35
	v_mul_f32_e32 v34, v35, v34
	v_cvt_pk_bf16_f32 v33, v33, v34
	global_store_dwordx2 v[70:71], v[32:33], off offset:96
	v_lshlrev_b32_e32 v32, 16, v78
	v_add_f32_e32 v28, v53, v28
	v_mul_f32_e32 v28, v28, v32
	v_and_b32_e32 v32, 0xffff0000, v78
	v_add_f32_e32 v29, v53, v29
	v_mul_f32_e32 v29, v29, v32
	v_cvt_pk_bf16_f32 v28, v28, v29
	v_lshlrev_b32_e32 v29, 16, v79
	v_add_f32_e32 v30, v53, v30
	v_mul_f32_e32 v29, v30, v29
	v_and_b32_e32 v30, 0xffff0000, v79
	v_add_f32_e32 v31, v53, v31
	v_mul_f32_e32 v30, v31, v30
	v_cvt_pk_bf16_f32 v29, v29, v30
	global_store_dwordx2 v[70:71], v[28:29], off offset:128
	v_lshlrev_b32_e32 v28, 16, v76
	v_add_f32_e32 v24, v53, v24
	v_mul_f32_e32 v24, v24, v28
	v_and_b32_e32 v28, 0xffff0000, v76
	v_add_f32_e32 v25, v53, v25
	v_mul_f32_e32 v25, v25, v28
	v_cvt_pk_bf16_f32 v24, v24, v25
	v_lshlrev_b32_e32 v25, 16, v77
	v_add_f32_e32 v26, v53, v26
	v_mul_f32_e32 v25, v26, v25
	v_and_b32_e32 v26, 0xffff0000, v77
	v_add_f32_e32 v27, v53, v27
	v_mul_f32_e32 v26, v27, v26
	v_cvt_pk_bf16_f32 v25, v25, v26
	global_store_dwordx2 v[70:71], v[24:25], off offset:160
	v_lshlrev_b32_e32 v24, 16, v74
	v_add_f32_e32 v20, v53, v20
	v_mul_f32_e32 v20, v20, v24
	v_and_b32_e32 v24, 0xffff0000, v74
	v_add_f32_e32 v21, v53, v21
	v_mul_f32_e32 v21, v21, v24
	v_cvt_pk_bf16_f32 v20, v20, v21
	v_lshlrev_b32_e32 v21, 16, v75
	v_add_f32_e32 v22, v53, v22
	v_mul_f32_e32 v21, v22, v21
	v_and_b32_e32 v22, 0xffff0000, v75
	v_add_f32_e32 v23, v53, v23
	v_mul_f32_e32 v22, v23, v22
	v_cvt_pk_bf16_f32 v21, v21, v22
	global_store_dwordx2 v[70:71], v[20:21], off offset:192
	v_lshlrev_b32_e32 v20, 16, v72
	v_add_f32_e32 v16, v53, v16
	v_mul_f32_e32 v16, v16, v20
	v_and_b32_e32 v20, 0xffff0000, v72
	v_add_f32_e32 v17, v53, v17
	v_mul_f32_e32 v17, v17, v20
	v_cvt_pk_bf16_f32 v16, v16, v17
	v_lshlrev_b32_e32 v17, 16, v73
	v_add_f32_e32 v18, v53, v18
	s_add_i32 s0, s0, 1
	s_mov_b64 s[2:3], 0x8000
	v_mul_f32_e32 v17, v18, v17
	v_and_b32_e32 v18, 0xffff0000, v73
	v_add_f32_e32 v19, v53, v19
	s_cmp_eq_u32 s0, 4
	v_lshl_add_u64 v[68:69], v[68:69], 0, s[2:3]
	v_mul_f32_e32 v18, v19, v18
	v_cvt_pk_bf16_f32 v17, v17, v18
	global_store_dwordx2 v[70:71], v[16:17], off offset:224
	s_barrier
	s_cbranch_scc0 .LBB0_194
	s_add_i32 s14, s14, s55
	s_cmpk_gt_i32 s14, 0xff
	s_cbranch_scc0 .LBB0_191
